# input-copy phase no longer materialises the f32 residual: the first residual GEMM epilogue reads the model input directly and writes x
# speedup vs baseline: 1.0035x; 1.0035x over previous
.LBB0_540:
	s_andn2_b64 vcc, exec, s[10:11]
	s_cbranch_vccnz .LBB0_514
	v_mbcnt_lo_u32_b32 v141, -1, 0
	v_mbcnt_hi_u32_b32 v141, -1, v141
	s_lshl_b32 s72, s81, 1
	s_add_i32 s72, s72, 0x20000
	s_cmp_eq_u32 s81, 0x1c00
	s_cselect_b32 s99, 0x800, 0
	s_add_i32 s72, s72, s99
	v_and_b32_e32 v132, 15, v141
	v_lshrrev_b32_e32 v133, 4, v141
	v_bfe_u32 v134, v141, 1, 3
	v_xor_b32_e32 v133, v133, v134
	v_lshlrev_b32_e32 v133, 4, v133
	v_lshl_add_u32 v132, v132, 7, v133
	v_add_u32_e32 v132, s72, v132
	v_xor_b32_e32 v133, 64, v132
	v_lshrrev_b32_e32 v134, 3, v141
	v_and_b32_e32 v135, 7, v141
	v_lshrrev_b32_e32 v148, 4, v141
	v_xor_b32_e32 v135, v135, v148
	v_lshlrev_b32_e32 v135, 4, v135
	v_lshl_add_u32 v134, v134, 7, v135
	v_add_u32_e32 v134, s72, v134
	v_xor_b32_e32 v135, 64, v134
	v_and_b32_e32 v148, 64, v151
	v_lshrrev_b32_e32 v140, 3, v141
	v_add_u32_e32 v140, v148, v140
	v_and_b32_e32 v148, 7, v141
	s_lshl_b32 s99, s23, 7
	v_lshlrev_b32_e32 v136, 4, v148
	v_lshl_add_u32 v136, v140, 12, v136
	v_add_u32_e32 v136, s99, v136
	v_add_u32_e32 v137, 0x8000, v136
	v_mov_b32_e32 v173, v136
	v_mov_b32_e32 v177, v137
	s_lshl_b32 s99, s23, 6
	v_lshlrev_b32_e32 v138, 3, v148
	v_lshl_add_u32 v138, v140, 11, v138
	v_add_u32_e32 v138, s99, v138
	v_add_u32_e32 v139, 0x4000, v138
	v_lshlrev_b32_e32 v140, 6, v140
	s_lshl_b32 s99, s20, 20
	s_lshl_b32 s72, s25, 10
	s_add_u32 s99, s99, s72
	s_add_u32 s84, s16, s99
	s_addc_u32 s85, s17, 0
	s_mov_b64 s[100:101], s[84:85]
	s_cmp_lg_u32 s3, 4
	s_cbranch_scc1 .Lep1_notfirst
	s_load_dwordx2 s[100:101], s[62:63], 0x0
	s_waitcnt lgkmcnt(0)
	s_add_u32 s100, s100, s99
	s_addc_u32 s101, s101, 0
.Lep1_notfirst:
	s_lshl_b32 s99, s20, 19
	s_lshl_b32 s72, s25, 9
	s_add_u32 s99, s99, s72
	s_add_u32 s10, s70, s99
	s_addc_u32 s11, s71, 0
	s_lshl_b32 s99, s20, 14
	s_lshl_b32 s72, s25, 2
	s_or_b32 s72, s72, s23
	s_lshl_b32 s72, s72, 2
	s_add_u32 s99, s99, s72
	s_add_u32 s78, s38, s99
	s_addc_u32 s79, s39, 0
	global_load_dwordx4 v[190:193], v136, s[100:101] nt
	global_load_dwordx4 v[194:197], v136, s[100:101] offset:512 nt
	global_load_dwordx4 v[198:201], v137, s[100:101] nt
	global_load_dwordx4 v[202:205], v137, s[100:101] offset:512 nt
	v_add_u32_e32 v136, 0x10000, v136
	v_add_u32_e32 v137, 0x10000, v137
	global_load_dwordx4 v[206:209], v136, s[100:101] nt
	global_load_dwordx4 v[210:213], v136, s[100:101] offset:512 nt
	global_load_dwordx4 v[214:217], v137, s[100:101] nt
	global_load_dwordx4 v[218:221], v137, s[100:101] offset:512 nt
	v_add_u32_e32 v136, 0x10000, v136
	v_add_u32_e32 v137, 0x10000, v137
	global_load_dwordx4 v[222:225], v136, s[100:101] nt
	global_load_dwordx4 v[226:229], v136, s[100:101] offset:512 nt
	global_load_dwordx4 v[230:233], v137, s[100:101] nt
	global_load_dwordx4 v[128:131], v137, s[100:101] offset:512 nt
	v_add_u32_e32 v136, 0x10000, v136
	v_add_u32_e32 v137, 0x10000, v137
	ds_write_b128 v132, v[124:127]
	ds_write_b128 v133, v[116:119]
	ds_read_b128 v[124:127], v134
	ds_read_b128 v[116:119], v135 offset:1024
	ds_write_b128 v132, v[108:111]
	ds_write_b128 v133, v[100:103]
	ds_read_b128 v[108:111], v134
	ds_read_b128 v[100:103], v135 offset:1024
	ds_write_b128 v132, v[120:123]
	ds_write_b128 v133, v[112:115]
	ds_read_b128 v[120:123], v134
	ds_read_b128 v[112:115], v135 offset:1024
	ds_write_b128 v132, v[104:107]
	ds_write_b128 v133, v[96:99]
	ds_read_b128 v[104:107], v134
	ds_read_b128 v[96:99], v135 offset:1024
	ds_write_b128 v132, v[92:95]
	ds_write_b128 v133, v[84:87]
	ds_read_b128 v[92:95], v134
	ds_read_b128 v[84:87], v135 offset:1024
	ds_write_b128 v132, v[76:79]
	ds_write_b128 v133, v[68:71]
	ds_read_b128 v[76:79], v134
	ds_read_b128 v[68:71], v135 offset:1024
	ds_write_b128 v132, v[88:91]
	ds_write_b128 v133, v[80:83]
	ds_read_b128 v[88:91], v134
	ds_read_b128 v[80:83], v135 offset:1024
	ds_write_b128 v132, v[72:75]
	ds_write_b128 v133, v[64:67]
	ds_read_b128 v[72:75], v134
	ds_read_b128 v[64:67], v135 offset:1024
	ds_write_b128 v132, v[60:63]
	ds_write_b128 v133, v[56:59]
	ds_read_b128 v[60:63], v134
	ds_read_b128 v[56:59], v135 offset:1024
	ds_write_b128 v132, v[44:47]
	ds_write_b128 v133, v[36:39]
	ds_read_b128 v[44:47], v134
	ds_read_b128 v[36:39], v135 offset:1024
	ds_write_b128 v132, v[52:55]
	ds_write_b128 v133, v[48:51]
	ds_read_b128 v[52:55], v134
	ds_read_b128 v[48:51], v135 offset:1024
	ds_write_b128 v132, v[40:43]
	ds_write_b128 v133, v[32:35]
	ds_read_b128 v[40:43], v134
	ds_read_b128 v[32:35], v135 offset:1024
	ds_write_b128 v132, v[28:31]
	ds_write_b128 v133, v[20:23]
	ds_read_b128 v[28:31], v134
	ds_read_b128 v[20:23], v135 offset:1024
	ds_write_b128 v132, v[12:15]
	ds_write_b128 v133, v[4:7]
	ds_read_b128 v[12:15], v134
	ds_read_b128 v[4:7], v135 offset:1024
	ds_write_b128 v132, v[24:27]
	ds_write_b128 v133, v[16:19]
	ds_read_b128 v[24:27], v134
	ds_read_b128 v[16:19], v135 offset:1024
	ds_write_b128 v132, v[8:11]
	ds_write_b128 v133, v[0:3]
	ds_read_b128 v[8:11], v134
	ds_read_b128 v[0:3], v135 offset:1024
	s_waitcnt lgkmcnt(0)
	s_waitcnt vmcnt(8)
	v_pk_fma_f32 v[124:125], s[82:83], v[124:125], v[190:191]
	v_pk_fma_f32 v[126:127], s[82:83], v[126:127], v[192:193]
	v_pk_fma_f32 v[108:109], s[82:83], v[108:109], v[194:195]
	v_pk_fma_f32 v[110:111], s[82:83], v[110:111], v[196:197]
	v_pk_fma_f32 v[116:117], s[82:83], v[116:117], v[198:199]
	v_pk_fma_f32 v[118:119], s[82:83], v[118:119], v[200:201]
	v_pk_fma_f32 v[100:101], s[82:83], v[100:101], v[202:203]
	v_pk_fma_f32 v[102:103], s[82:83], v[102:103], v[204:205]
	global_store_dwordx4 v173, v[124:127], s[84:85] nt
	v_cvt_pk_bf16_f32 v164, v124, v125
	v_cvt_pk_bf16_f32 v165, v126, v127
	v_mul_f32_e32 v132, v124, v124
	v_fmac_f32_e32 v132, v125, v125
	v_fmac_f32_e32 v132, v126, v126
	v_fmac_f32_e32 v132, v127, v127
	global_store_dwordx2 v138, v[164:165], s[10:11]
	global_store_dwordx4 v173, v[108:111], s[84:85] offset:512 nt
	v_cvt_pk_bf16_f32 v166, v108, v109
	v_cvt_pk_bf16_f32 v167, v110, v111
	v_fmac_f32_e32 v132, v108, v108
	v_fmac_f32_e32 v132, v109, v109
	v_fmac_f32_e32 v132, v110, v110
	v_fmac_f32_e32 v132, v111, v111
	global_store_dwordx2 v138, v[166:167], s[10:11] offset:256
	global_store_dwordx4 v177, v[116:119], s[84:85] nt
	v_cvt_pk_bf16_f32 v174, v116, v117
	v_cvt_pk_bf16_f32 v175, v118, v119
	v_mul_f32_e32 v133, v116, v116
	v_fmac_f32_e32 v133, v117, v117
	v_fmac_f32_e32 v133, v118, v118
	v_fmac_f32_e32 v133, v119, v119
	global_store_dwordx2 v139, v[174:175], s[10:11]
	global_store_dwordx4 v177, v[100:103], s[84:85] offset:512 nt
	v_cvt_pk_bf16_f32 v142, v100, v101
	v_cvt_pk_bf16_f32 v143, v102, v103
	v_fmac_f32_e32 v133, v100, v100
	v_fmac_f32_e32 v133, v101, v101
	v_fmac_f32_e32 v133, v102, v102
	v_fmac_f32_e32 v133, v103, v103
	global_store_dwordx2 v139, v[142:143], s[10:11] offset:256
	s_nop 1
	v_add_f32_dpp v132, v132, v132 quad_perm:[1,0,3,2] row_mask:0xf bank_mask:0xf
	v_add_f32_dpp v133, v133, v133 quad_perm:[1,0,3,2] row_mask:0xf bank_mask:0xf
	s_nop 0
	v_add_f32_dpp v132, v132, v132 quad_perm:[2,3,0,1] row_mask:0xf bank_mask:0xf
	v_add_f32_dpp v133, v133, v133 quad_perm:[2,3,0,1] row_mask:0xf bank_mask:0xf
	s_nop 0
	v_add_f32_dpp v132, v132, v132 row_half_mirror row_mask:0xf bank_mask:0xf
	v_add_f32_dpp v133, v133, v133 row_half_mirror row_mask:0xf bank_mask:0xf
	s_nop 0
	s_mov_b32 exec_lo, 0x1010101
	s_mov_b32 exec_hi, 0x1010101
	global_store_dword v140, v132, s[78:79]
	global_store_dword v140, v133, s[78:79] offset:512
	s_mov_b64 exec, -1
	v_add_u32_e32 v173, 0x10000, v173
	v_add_u32_e32 v177, 0x10000, v177
	v_add_u32_e32 v138, 0x8000, v138
	v_add_u32_e32 v139, 0x8000, v139
	global_load_dwordx4 v[190:193], v136, s[100:101] nt
	global_load_dwordx4 v[194:197], v136, s[100:101] offset:512 nt
	global_load_dwordx4 v[198:201], v137, s[100:101] nt
	global_load_dwordx4 v[202:205], v137, s[100:101] offset:512 nt
	v_add_u32_e32 v136, 0x50000, v136
	v_add_u32_e32 v137, 0x50000, v137
	s_waitcnt vmcnt(18)
	v_pk_fma_f32 v[120:121], s[82:83], v[120:121], v[206:207]
	v_pk_fma_f32 v[122:123], s[82:83], v[122:123], v[208:209]
	v_pk_fma_f32 v[104:105], s[82:83], v[104:105], v[210:211]
	v_pk_fma_f32 v[106:107], s[82:83], v[106:107], v[212:213]
	v_pk_fma_f32 v[112:113], s[82:83], v[112:113], v[214:215]
	v_pk_fma_f32 v[114:115], s[82:83], v[114:115], v[216:217]
	v_pk_fma_f32 v[96:97], s[82:83], v[96:97], v[218:219]
	v_pk_fma_f32 v[98:99], s[82:83], v[98:99], v[220:221]
	global_store_dwordx4 v173, v[120:123], s[84:85] nt
	v_cvt_pk_bf16_f32 v164, v120, v121
	v_cvt_pk_bf16_f32 v165, v122, v123
	v_mul_f32_e32 v134, v120, v120
	v_fmac_f32_e32 v134, v121, v121
	v_fmac_f32_e32 v134, v122, v122
	v_fmac_f32_e32 v134, v123, v123
	global_store_dwordx2 v138, v[164:165], s[10:11]
	global_store_dwordx4 v173, v[104:107], s[84:85] offset:512 nt
	v_cvt_pk_bf16_f32 v166, v104, v105
	v_cvt_pk_bf16_f32 v167, v106, v107
	v_fmac_f32_e32 v134, v104, v104
	v_fmac_f32_e32 v134, v105, v105
	v_fmac_f32_e32 v134, v106, v106
	v_fmac_f32_e32 v134, v107, v107
	global_store_dwordx2 v138, v[166:167], s[10:11] offset:256
	global_store_dwordx4 v177, v[112:115], s[84:85] nt
	v_cvt_pk_bf16_f32 v174, v112, v113
	v_cvt_pk_bf16_f32 v175, v114, v115
	v_mul_f32_e32 v135, v112, v112
	v_fmac_f32_e32 v135, v113, v113
	v_fmac_f32_e32 v135, v114, v114
	v_fmac_f32_e32 v135, v115, v115
	global_store_dwordx2 v139, v[174:175], s[10:11]
	global_store_dwordx4 v177, v[96:99], s[84:85] offset:512 nt
	v_cvt_pk_bf16_f32 v142, v96, v97
	v_cvt_pk_bf16_f32 v143, v98, v99
	v_fmac_f32_e32 v135, v96, v96
	v_fmac_f32_e32 v135, v97, v97
	v_fmac_f32_e32 v135, v98, v98
	v_fmac_f32_e32 v135, v99, v99
	global_store_dwordx2 v139, v[142:143], s[10:11] offset:256
	s_nop 1
	v_add_f32_dpp v134, v134, v134 quad_perm:[1,0,3,2] row_mask:0xf bank_mask:0xf
	v_add_f32_dpp v135, v135, v135 quad_perm:[1,0,3,2] row_mask:0xf bank_mask:0xf
	s_nop 0
	v_add_f32_dpp v134, v134, v134 quad_perm:[2,3,0,1] row_mask:0xf bank_mask:0xf
	v_add_f32_dpp v135, v135, v135 quad_perm:[2,3,0,1] row_mask:0xf bank_mask:0xf
	s_nop 0
	v_add_f32_dpp v134, v134, v134 row_half_mirror row_mask:0xf bank_mask:0xf
	v_add_f32_dpp v135, v135, v135 row_half_mirror row_mask:0xf bank_mask:0xf
	s_nop 0
	s_mov_b32 exec_lo, 0x1010101
	s_mov_b32 exec_hi, 0x1010101
	global_store_dword v140, v134, s[78:79] offset:1024
	global_store_dword v140, v135, s[78:79] offset:1536
	s_mov_b64 exec, -1
	v_add_u32_e32 v173, 0x10000, v173
	v_add_u32_e32 v177, 0x10000, v177
	v_add_u32_e32 v138, 0x8000, v138
	v_add_u32_e32 v139, 0x8000, v139
	global_load_dwordx4 v[206:209], v136, s[100:101] nt
	global_load_dwordx4 v[210:213], v136, s[100:101] offset:512 nt
	global_load_dwordx4 v[214:217], v137, s[100:101] nt
	global_load_dwordx4 v[218:221], v137, s[100:101] offset:512 nt
	v_add_u32_e32 v136, 0x10000, v136
	v_add_u32_e32 v137, 0x10000, v137
	s_waitcnt vmcnt(28)
	v_pk_fma_f32 v[92:93], s[82:83], v[92:93], v[222:223]
	v_pk_fma_f32 v[94:95], s[82:83], v[94:95], v[224:225]
	v_pk_fma_f32 v[76:77], s[82:83], v[76:77], v[226:227]
	v_pk_fma_f32 v[78:79], s[82:83], v[78:79], v[228:229]
	v_pk_fma_f32 v[84:85], s[82:83], v[84:85], v[230:231]
	v_pk_fma_f32 v[86:87], s[82:83], v[86:87], v[232:233]
	v_pk_fma_f32 v[68:69], s[82:83], v[68:69], v[128:129]
	v_pk_fma_f32 v[70:71], s[82:83], v[70:71], v[130:131]
	global_store_dwordx4 v173, v[92:95], s[84:85] nt
	v_cvt_pk_bf16_f32 v164, v92, v93
	v_cvt_pk_bf16_f32 v165, v94, v95
	v_mul_f32_e32 v132, v92, v92
	v_fmac_f32_e32 v132, v93, v93
	v_fmac_f32_e32 v132, v94, v94
	v_fmac_f32_e32 v132, v95, v95
	global_store_dwordx2 v138, v[164:165], s[10:11]
	global_store_dwordx4 v173, v[76:79], s[84:85] offset:512 nt
	v_cvt_pk_bf16_f32 v166, v76, v77
	v_cvt_pk_bf16_f32 v167, v78, v79
	v_fmac_f32_e32 v132, v76, v76
	v_fmac_f32_e32 v132, v77, v77
	v_fmac_f32_e32 v132, v78, v78
	v_fmac_f32_e32 v132, v79, v79
	global_store_dwordx2 v138, v[166:167], s[10:11] offset:256
	global_store_dwordx4 v177, v[84:87], s[84:85] nt
	v_cvt_pk_bf16_f32 v174, v84, v85
	v_cvt_pk_bf16_f32 v175, v86, v87
	v_mul_f32_e32 v133, v84, v84
	v_fmac_f32_e32 v133, v85, v85
	v_fmac_f32_e32 v133, v86, v86
	v_fmac_f32_e32 v133, v87, v87
	global_store_dwordx2 v139, v[174:175], s[10:11]
	global_store_dwordx4 v177, v[68:71], s[84:85] offset:512 nt
	v_cvt_pk_bf16_f32 v142, v68, v69
	v_cvt_pk_bf16_f32 v143, v70, v71
	v_fmac_f32_e32 v133, v68, v68
	v_fmac_f32_e32 v133, v69, v69
	v_fmac_f32_e32 v133, v70, v70
	v_fmac_f32_e32 v133, v71, v71
	global_store_dwordx2 v139, v[142:143], s[10:11] offset:256
	s_nop 1
	v_add_f32_dpp v132, v132, v132 quad_perm:[1,0,3,2] row_mask:0xf bank_mask:0xf
	v_add_f32_dpp v133, v133, v133 quad_perm:[1,0,3,2] row_mask:0xf bank_mask:0xf
	s_nop 0
	v_add_f32_dpp v132, v132, v132 quad_perm:[2,3,0,1] row_mask:0xf bank_mask:0xf
	v_add_f32_dpp v133, v133, v133 quad_perm:[2,3,0,1] row_mask:0xf bank_mask:0xf
	s_nop 0
	v_add_f32_dpp v132, v132, v132 row_half_mirror row_mask:0xf bank_mask:0xf
	v_add_f32_dpp v133, v133, v133 row_half_mirror row_mask:0xf bank_mask:0xf
	s_nop 0
	s_mov_b32 exec_lo, 0x1010101
	s_mov_b32 exec_hi, 0x1010101
	global_store_dword v140, v132, s[78:79] offset:2048
	global_store_dword v140, v133, s[78:79] offset:2560
	s_mov_b64 exec, -1
	v_add_u32_e32 v173, 0x10000, v173
	v_add_u32_e32 v177, 0x10000, v177
	v_add_u32_e32 v138, 0x8000, v138
	v_add_u32_e32 v139, 0x8000, v139
	global_load_dwordx4 v[222:225], v136, s[100:101] nt
	global_load_dwordx4 v[226:229], v136, s[100:101] offset:512 nt
	global_load_dwordx4 v[230:233], v137, s[100:101] nt
	global_load_dwordx4 v[128:131], v137, s[100:101] offset:512 nt
	v_add_u32_e32 v136, 0x10000, v136
	v_add_u32_e32 v137, 0x10000, v137
	s_waitcnt vmcnt(28)
	v_pk_fma_f32 v[88:89], s[82:83], v[88:89], v[190:191]
	v_pk_fma_f32 v[90:91], s[82:83], v[90:91], v[192:193]
	v_pk_fma_f32 v[72:73], s[82:83], v[72:73], v[194:195]
	v_pk_fma_f32 v[74:75], s[82:83], v[74:75], v[196:197]
	v_pk_fma_f32 v[80:81], s[82:83], v[80:81], v[198:199]
	v_pk_fma_f32 v[82:83], s[82:83], v[82:83], v[200:201]
	v_pk_fma_f32 v[64:65], s[82:83], v[64:65], v[202:203]
	v_pk_fma_f32 v[66:67], s[82:83], v[66:67], v[204:205]
	global_store_dwordx4 v173, v[88:91], s[84:85] nt
	v_cvt_pk_bf16_f32 v164, v88, v89
	v_cvt_pk_bf16_f32 v165, v90, v91
	v_mul_f32_e32 v134, v88, v88
	v_fmac_f32_e32 v134, v89, v89
	v_fmac_f32_e32 v134, v90, v90
	v_fmac_f32_e32 v134, v91, v91
	global_store_dwordx2 v138, v[164:165], s[10:11]
	global_store_dwordx4 v173, v[72:75], s[84:85] offset:512 nt
	v_cvt_pk_bf16_f32 v166, v72, v73
	v_cvt_pk_bf16_f32 v167, v74, v75
	v_fmac_f32_e32 v134, v72, v72
	v_fmac_f32_e32 v134, v73, v73
	v_fmac_f32_e32 v134, v74, v74
	v_fmac_f32_e32 v134, v75, v75
	global_store_dwordx2 v138, v[166:167], s[10:11] offset:256
	global_store_dwordx4 v177, v[80:83], s[84:85] nt
	v_cvt_pk_bf16_f32 v174, v80, v81
	v_cvt_pk_bf16_f32 v175, v82, v83
	v_mul_f32_e32 v135, v80, v80
	v_fmac_f32_e32 v135, v81, v81
	v_fmac_f32_e32 v135, v82, v82
	v_fmac_f32_e32 v135, v83, v83
	global_store_dwordx2 v139, v[174:175], s[10:11]
	global_store_dwordx4 v177, v[64:67], s[84:85] offset:512 nt
	v_cvt_pk_bf16_f32 v142, v64, v65
	v_cvt_pk_bf16_f32 v143, v66, v67
	v_fmac_f32_e32 v135, v64, v64
	v_fmac_f32_e32 v135, v65, v65
	v_fmac_f32_e32 v135, v66, v66
	v_fmac_f32_e32 v135, v67, v67
	global_store_dwordx2 v139, v[142:143], s[10:11] offset:256
	s_nop 1
	v_add_f32_dpp v134, v134, v134 quad_perm:[1,0,3,2] row_mask:0xf bank_mask:0xf
	v_add_f32_dpp v135, v135, v135 quad_perm:[1,0,3,2] row_mask:0xf bank_mask:0xf
	s_nop 0
	v_add_f32_dpp v134, v134, v134 quad_perm:[2,3,0,1] row_mask:0xf bank_mask:0xf
	v_add_f32_dpp v135, v135, v135 quad_perm:[2,3,0,1] row_mask:0xf bank_mask:0xf
	s_nop 0
	v_add_f32_dpp v134, v134, v134 row_half_mirror row_mask:0xf bank_mask:0xf
	v_add_f32_dpp v135, v135, v135 row_half_mirror row_mask:0xf bank_mask:0xf
	s_nop 0
	s_mov_b32 exec_lo, 0x1010101
	s_mov_b32 exec_hi, 0x1010101
	global_store_dword v140, v134, s[78:79] offset:3072
	global_store_dword v140, v135, s[78:79] offset:3584
	s_mov_b64 exec, -1
	v_add_u32_e32 v173, 0x50000, v173
	v_add_u32_e32 v177, 0x50000, v177
	v_add_u32_e32 v138, 0x28000, v138
	v_add_u32_e32 v139, 0x28000, v139
	s_add_u32 s78, s78, 0x2000
	s_addc_u32 s79, s79, 0
	global_load_dwordx4 v[190:193], v136, s[100:101] nt
	global_load_dwordx4 v[194:197], v136, s[100:101] offset:512 nt
	global_load_dwordx4 v[198:201], v137, s[100:101] nt
	global_load_dwordx4 v[202:205], v137, s[100:101] offset:512 nt
	v_add_u32_e32 v136, 0x10000, v136
	v_add_u32_e32 v137, 0x10000, v137
	s_waitcnt vmcnt(28)
	v_pk_fma_f32 v[60:61], s[82:83], v[60:61], v[206:207]
	v_pk_fma_f32 v[62:63], s[82:83], v[62:63], v[208:209]
	v_pk_fma_f32 v[44:45], s[82:83], v[44:45], v[210:211]
	v_pk_fma_f32 v[46:47], s[82:83], v[46:47], v[212:213]
	v_pk_fma_f32 v[56:57], s[82:83], v[56:57], v[214:215]
	v_pk_fma_f32 v[58:59], s[82:83], v[58:59], v[216:217]
	v_pk_fma_f32 v[36:37], s[82:83], v[36:37], v[218:219]
	v_pk_fma_f32 v[38:39], s[82:83], v[38:39], v[220:221]
	global_store_dwordx4 v173, v[60:63], s[84:85] nt
	v_cvt_pk_bf16_f32 v164, v60, v61
	v_cvt_pk_bf16_f32 v165, v62, v63
	v_mul_f32_e32 v132, v60, v60
	v_fmac_f32_e32 v132, v61, v61
	v_fmac_f32_e32 v132, v62, v62
	v_fmac_f32_e32 v132, v63, v63
	global_store_dwordx2 v138, v[164:165], s[10:11]
	global_store_dwordx4 v173, v[44:47], s[84:85] offset:512 nt
	v_cvt_pk_bf16_f32 v166, v44, v45
	v_cvt_pk_bf16_f32 v167, v46, v47
	v_fmac_f32_e32 v132, v44, v44
	v_fmac_f32_e32 v132, v45, v45
	v_fmac_f32_e32 v132, v46, v46
	v_fmac_f32_e32 v132, v47, v47
	global_store_dwordx2 v138, v[166:167], s[10:11] offset:256
	global_store_dwordx4 v177, v[56:59], s[84:85] nt
	v_cvt_pk_bf16_f32 v174, v56, v57
	v_cvt_pk_bf16_f32 v175, v58, v59
	v_mul_f32_e32 v133, v56, v56
	v_fmac_f32_e32 v133, v57, v57
	v_fmac_f32_e32 v133, v58, v58
	v_fmac_f32_e32 v133, v59, v59
	global_store_dwordx2 v139, v[174:175], s[10:11]
	global_store_dwordx4 v177, v[36:39], s[84:85] offset:512 nt
	v_cvt_pk_bf16_f32 v142, v36, v37
	v_cvt_pk_bf16_f32 v143, v38, v39
	v_fmac_f32_e32 v133, v36, v36
	v_fmac_f32_e32 v133, v37, v37
	v_fmac_f32_e32 v133, v38, v38
	v_fmac_f32_e32 v133, v39, v39
	global_store_dwordx2 v139, v[142:143], s[10:11] offset:256
	s_nop 1
	v_add_f32_dpp v132, v132, v132 quad_perm:[1,0,3,2] row_mask:0xf bank_mask:0xf
	v_add_f32_dpp v133, v133, v133 quad_perm:[1,0,3,2] row_mask:0xf bank_mask:0xf
	s_nop 0
	v_add_f32_dpp v132, v132, v132 quad_perm:[2,3,0,1] row_mask:0xf bank_mask:0xf
	v_add_f32_dpp v133, v133, v133 quad_perm:[2,3,0,1] row_mask:0xf bank_mask:0xf
	s_nop 0
	v_add_f32_dpp v132, v132, v132 row_half_mirror row_mask:0xf bank_mask:0xf
	v_add_f32_dpp v133, v133, v133 row_half_mirror row_mask:0xf bank_mask:0xf
	s_nop 0
	s_mov_b32 exec_lo, 0x1010101
	s_mov_b32 exec_hi, 0x1010101
	global_store_dword v140, v132, s[78:79]
	global_store_dword v140, v133, s[78:79] offset:512
	s_mov_b64 exec, -1
	v_add_u32_e32 v173, 0x10000, v173
	v_add_u32_e32 v177, 0x10000, v177
	v_add_u32_e32 v138, 0x8000, v138
	v_add_u32_e32 v139, 0x8000, v139
	global_load_dwordx4 v[206:209], v136, s[100:101] nt
	global_load_dwordx4 v[210:213], v136, s[100:101] offset:512 nt
	global_load_dwordx4 v[214:217], v137, s[100:101] nt
	global_load_dwordx4 v[218:221], v137, s[100:101] offset:512 nt
	s_waitcnt vmcnt(28)
	v_pk_fma_f32 v[52:53], s[82:83], v[52:53], v[222:223]
	v_pk_fma_f32 v[54:55], s[82:83], v[54:55], v[224:225]
	v_pk_fma_f32 v[40:41], s[82:83], v[40:41], v[226:227]
	v_pk_fma_f32 v[42:43], s[82:83], v[42:43], v[228:229]
	v_pk_fma_f32 v[48:49], s[82:83], v[48:49], v[230:231]
	v_pk_fma_f32 v[50:51], s[82:83], v[50:51], v[232:233]
	v_pk_fma_f32 v[32:33], s[82:83], v[32:33], v[128:129]
	v_pk_fma_f32 v[34:35], s[82:83], v[34:35], v[130:131]
	global_store_dwordx4 v173, v[52:55], s[84:85] nt
	v_cvt_pk_bf16_f32 v164, v52, v53
	v_cvt_pk_bf16_f32 v165, v54, v55
	v_mul_f32_e32 v134, v52, v52
	v_fmac_f32_e32 v134, v53, v53
	v_fmac_f32_e32 v134, v54, v54
	v_fmac_f32_e32 v134, v55, v55
	global_store_dwordx2 v138, v[164:165], s[10:11]
	global_store_dwordx4 v173, v[40:43], s[84:85] offset:512 nt
	v_cvt_pk_bf16_f32 v166, v40, v41
	v_cvt_pk_bf16_f32 v167, v42, v43
	v_fmac_f32_e32 v134, v40, v40
	v_fmac_f32_e32 v134, v41, v41
	v_fmac_f32_e32 v134, v42, v42
	v_fmac_f32_e32 v134, v43, v43
	global_store_dwordx2 v138, v[166:167], s[10:11] offset:256
	global_store_dwordx4 v177, v[48:51], s[84:85] nt
	v_cvt_pk_bf16_f32 v174, v48, v49
	v_cvt_pk_bf16_f32 v175, v50, v51
	v_mul_f32_e32 v135, v48, v48
	v_fmac_f32_e32 v135, v49, v49
	v_fmac_f32_e32 v135, v50, v50
	v_fmac_f32_e32 v135, v51, v51
	global_store_dwordx2 v139, v[174:175], s[10:11]
	global_store_dwordx4 v177, v[32:35], s[84:85] offset:512 nt
	v_cvt_pk_bf16_f32 v142, v32, v33
	v_cvt_pk_bf16_f32 v143, v34, v35
	v_fmac_f32_e32 v135, v32, v32
	v_fmac_f32_e32 v135, v33, v33
	v_fmac_f32_e32 v135, v34, v34
	v_fmac_f32_e32 v135, v35, v35
	global_store_dwordx2 v139, v[142:143], s[10:11] offset:256
	s_nop 1
	v_add_f32_dpp v134, v134, v134 quad_perm:[1,0,3,2] row_mask:0xf bank_mask:0xf
	v_add_f32_dpp v135, v135, v135 quad_perm:[1,0,3,2] row_mask:0xf bank_mask:0xf
	s_nop 0
	v_add_f32_dpp v134, v134, v134 quad_perm:[2,3,0,1] row_mask:0xf bank_mask:0xf
	v_add_f32_dpp v135, v135, v135 quad_perm:[2,3,0,1] row_mask:0xf bank_mask:0xf
	s_nop 0
	v_add_f32_dpp v134, v134, v134 row_half_mirror row_mask:0xf bank_mask:0xf
	v_add_f32_dpp v135, v135, v135 row_half_mirror row_mask:0xf bank_mask:0xf
	s_nop 0
	s_mov_b32 exec_lo, 0x1010101
	s_mov_b32 exec_hi, 0x1010101
	global_store_dword v140, v134, s[78:79] offset:1024
	global_store_dword v140, v135, s[78:79] offset:1536
	s_mov_b64 exec, -1
	v_add_u32_e32 v173, 0x10000, v173
	v_add_u32_e32 v177, 0x10000, v177
	v_add_u32_e32 v138, 0x8000, v138
	v_add_u32_e32 v139, 0x8000, v139
	s_waitcnt vmcnt(24)
	v_pk_fma_f32 v[28:29], s[82:83], v[28:29], v[190:191]
	v_pk_fma_f32 v[30:31], s[82:83], v[30:31], v[192:193]
	v_pk_fma_f32 v[12:13], s[82:83], v[12:13], v[194:195]
	v_pk_fma_f32 v[14:15], s[82:83], v[14:15], v[196:197]
	v_pk_fma_f32 v[20:21], s[82:83], v[20:21], v[198:199]
	v_pk_fma_f32 v[22:23], s[82:83], v[22:23], v[200:201]
	v_pk_fma_f32 v[4:5], s[82:83], v[4:5], v[202:203]
	v_pk_fma_f32 v[6:7], s[82:83], v[6:7], v[204:205]
	global_store_dwordx4 v173, v[28:31], s[84:85] nt
	v_cvt_pk_bf16_f32 v164, v28, v29
	v_cvt_pk_bf16_f32 v165, v30, v31
	v_mul_f32_e32 v132, v28, v28
	v_fmac_f32_e32 v132, v29, v29
	v_fmac_f32_e32 v132, v30, v30
	v_fmac_f32_e32 v132, v31, v31
	global_store_dwordx2 v138, v[164:165], s[10:11]
	global_store_dwordx4 v173, v[12:15], s[84:85] offset:512 nt
	v_cvt_pk_bf16_f32 v166, v12, v13
	v_cvt_pk_bf16_f32 v167, v14, v15
	v_fmac_f32_e32 v132, v12, v12
	v_fmac_f32_e32 v132, v13, v13
	v_fmac_f32_e32 v132, v14, v14
	v_fmac_f32_e32 v132, v15, v15
	global_store_dwordx2 v138, v[166:167], s[10:11] offset:256
	global_store_dwordx4 v177, v[20:23], s[84:85] nt
	v_cvt_pk_bf16_f32 v174, v20, v21
	v_cvt_pk_bf16_f32 v175, v22, v23
	v_mul_f32_e32 v133, v20, v20
	v_fmac_f32_e32 v133, v21, v21
	v_fmac_f32_e32 v133, v22, v22
	v_fmac_f32_e32 v133, v23, v23
	global_store_dwordx2 v139, v[174:175], s[10:11]
	global_store_dwordx4 v177, v[4:7], s[84:85] offset:512 nt
	v_cvt_pk_bf16_f32 v142, v4, v5
	v_cvt_pk_bf16_f32 v143, v6, v7
	v_fmac_f32_e32 v133, v4, v4
	v_fmac_f32_e32 v133, v5, v5
	v_fmac_f32_e32 v133, v6, v6
	v_fmac_f32_e32 v133, v7, v7
	global_store_dwordx2 v139, v[142:143], s[10:11] offset:256
	s_nop 1
	v_add_f32_dpp v132, v132, v132 quad_perm:[1,0,3,2] row_mask:0xf bank_mask:0xf
	v_add_f32_dpp v133, v133, v133 quad_perm:[1,0,3,2] row_mask:0xf bank_mask:0xf
	s_nop 0
	v_add_f32_dpp v132, v132, v132 quad_perm:[2,3,0,1] row_mask:0xf bank_mask:0xf
	v_add_f32_dpp v133, v133, v133 quad_perm:[2,3,0,1] row_mask:0xf bank_mask:0xf
	s_nop 0
	v_add_f32_dpp v132, v132, v132 row_half_mirror row_mask:0xf bank_mask:0xf
	v_add_f32_dpp v133, v133, v133 row_half_mirror row_mask:0xf bank_mask:0xf
	s_nop 0
	s_mov_b32 exec_lo, 0x1010101
	s_mov_b32 exec_hi, 0x1010101
	global_store_dword v140, v132, s[78:79] offset:2048
	global_store_dword v140, v133, s[78:79] offset:2560
	s_mov_b64 exec, -1
	v_add_u32_e32 v173, 0x10000, v173
	v_add_u32_e32 v177, 0x10000, v177
	v_add_u32_e32 v138, 0x8000, v138
	v_add_u32_e32 v139, 0x8000, v139
	s_waitcnt vmcnt(20)
	v_pk_fma_f32 v[24:25], s[82:83], v[24:25], v[206:207]
	v_pk_fma_f32 v[26:27], s[82:83], v[26:27], v[208:209]
	v_pk_fma_f32 v[8:9], s[82:83], v[8:9], v[210:211]
	v_pk_fma_f32 v[10:11], s[82:83], v[10:11], v[212:213]
	v_pk_fma_f32 v[16:17], s[82:83], v[16:17], v[214:215]
	v_pk_fma_f32 v[18:19], s[82:83], v[18:19], v[216:217]
	v_pk_fma_f32 v[0:1], s[82:83], v[0:1], v[218:219]
	v_pk_fma_f32 v[2:3], s[82:83], v[2:3], v[220:221]
	global_store_dwordx4 v173, v[24:27], s[84:85] nt
	v_cvt_pk_bf16_f32 v164, v24, v25
	v_cvt_pk_bf16_f32 v165, v26, v27
	v_mul_f32_e32 v134, v24, v24
	v_fmac_f32_e32 v134, v25, v25
	v_fmac_f32_e32 v134, v26, v26
	v_fmac_f32_e32 v134, v27, v27
	global_store_dwordx2 v138, v[164:165], s[10:11]
	global_store_dwordx4 v173, v[8:11], s[84:85] offset:512 nt
	v_cvt_pk_bf16_f32 v166, v8, v9
	v_cvt_pk_bf16_f32 v167, v10, v11
	v_fmac_f32_e32 v134, v8, v8
	v_fmac_f32_e32 v134, v9, v9
	v_fmac_f32_e32 v134, v10, v10
	v_fmac_f32_e32 v134, v11, v11
	global_store_dwordx2 v138, v[166:167], s[10:11] offset:256
	global_store_dwordx4 v177, v[16:19], s[84:85] nt
	v_cvt_pk_bf16_f32 v174, v16, v17
	v_cvt_pk_bf16_f32 v175, v18, v19
	v_mul_f32_e32 v135, v16, v16
	v_fmac_f32_e32 v135, v17, v17
	v_fmac_f32_e32 v135, v18, v18
	v_fmac_f32_e32 v135, v19, v19
	global_store_dwordx2 v139, v[174:175], s[10:11]
	global_store_dwordx4 v177, v[0:3], s[84:85] offset:512 nt
	v_cvt_pk_bf16_f32 v142, v0, v1
	v_cvt_pk_bf16_f32 v143, v2, v3
	v_fmac_f32_e32 v135, v0, v0
	v_fmac_f32_e32 v135, v1, v1
	v_fmac_f32_e32 v135, v2, v2
	v_fmac_f32_e32 v135, v3, v3
	global_store_dwordx2 v139, v[142:143], s[10:11] offset:256
	s_nop 1
	v_add_f32_dpp v134, v134, v134 quad_perm:[1,0,3,2] row_mask:0xf bank_mask:0xf
	v_add_f32_dpp v135, v135, v135 quad_perm:[1,0,3,2] row_mask:0xf bank_mask:0xf
	s_nop 0
	v_add_f32_dpp v134, v134, v134 quad_perm:[2,3,0,1] row_mask:0xf bank_mask:0xf
	v_add_f32_dpp v135, v135, v135 quad_perm:[2,3,0,1] row_mask:0xf bank_mask:0xf
	s_nop 0
	v_add_f32_dpp v134, v134, v134 row_half_mirror row_mask:0xf bank_mask:0xf
	v_add_f32_dpp v135, v135, v135 row_half_mirror row_mask:0xf bank_mask:0xf
	s_nop 0
	s_mov_b32 exec_lo, 0x1010101
	s_mov_b32 exec_hi, 0x1010101
	global_store_dword v140, v134, s[78:79] offset:3072
	global_store_dword v140, v135, s[78:79] offset:3584
	s_mov_b64 exec, -1
	s_branch .LBB0_514

.LBB0_563:
	v_lshl_add_u64 v[34:35], v[4:5], 0, v[148:149]
	s_waitcnt lgkmcnt(0)
	global_load_dwordx4 v[26:29], v[34:35], off
	v_lshl_add_u64 v[42:43], v[8:9], 0, v[148:149]
	s_waitcnt vmcnt(0)
	v_cvt_pk_bf16_f32 v30, v26, v27
	v_cvt_pk_bf16_f32 v31, v28, v29
	global_store_dwordx2 v[6:7], v[30:31], off offset:-1024
	global_load_dwordx4 v[30:33], v[34:35], off offset:1024
	v_mul_f32_e32 v25, v27, v27
	v_mul_f32_e32 v27, v29, v29
	v_fmac_f32_e32 v25, v26, v26
	v_fmac_f32_e32 v27, v28, v28
	v_add_f32_e32 v25, v25, v27
	s_waitcnt vmcnt(0)
	v_cvt_pk_bf16_f32 v38, v30, v31
	v_cvt_pk_bf16_f32 v39, v32, v33
	global_store_dwordx2 v[6:7], v[38:39], off offset:-512
	global_load_dwordx4 v[38:41], v[34:35], off offset:2048
	v_mul_f32_e32 v26, v31, v31
	v_mul_f32_e32 v27, v33, v33
	v_fmac_f32_e32 v26, v30, v30
	v_fmac_f32_e32 v27, v32, v32
	v_add_f32_e32 v26, v26, v27
	v_add_f32_e32 v25, v25, v26
	s_waitcnt vmcnt(0)
	v_cvt_pk_bf16_f32 v46, v38, v39
	v_cvt_pk_bf16_f32 v47, v40, v41
	global_store_dwordx2 v[6:7], v[46:47], off
	global_load_dwordx4 v[46:49], v[34:35], off offset:3072
	v_mul_f32_e32 v26, v39, v39
	v_mul_f32_e32 v27, v41, v41
	v_fmac_f32_e32 v26, v38, v38
	v_fmac_f32_e32 v27, v40, v40
	v_add_f32_e32 v26, v26, v27
	v_add_f32_e32 v25, v25, v26
	s_waitcnt vmcnt(0)
	v_mul_f32_e32 v26, v47, v47
	v_mul_f32_e32 v27, v49, v49
	v_fmac_f32_e32 v26, v46, v46
	v_fmac_f32_e32 v27, v48, v48
	v_add_f32_e32 v26, v26, v27
	v_add_f32_e32 v25, v25, v26
	ds_bpermute_b32 v26, v18, v25
	v_cvt_pk_bf16_f32 v28, v46, v47
	v_cvt_pk_bf16_f32 v29, v48, v49
	global_store_dwordx2 v[6:7], v[28:29], off offset:512
	s_waitcnt lgkmcnt(0)
	v_add_f32_e32 v25, v25, v26
	ds_bpermute_b32 v26, v19, v25
	s_waitcnt lgkmcnt(0)
	v_add_f32_e32 v25, v25, v26
	ds_bpermute_b32 v26, v20, v25
	s_waitcnt lgkmcnt(0)
	v_add_f32_e32 v25, v25, v26
	ds_bpermute_b32 v26, v21, v25
	s_waitcnt lgkmcnt(0)
	v_add_f32_e32 v25, v25, v26
	ds_bpermute_b32 v26, v22, v25
	s_waitcnt lgkmcnt(0)
	v_add_f32_e32 v25, v25, v26
	ds_bpermute_b32 v26, v23, v25
	s_and_saveexec_b64 s[6:7], vcc
	s_cbranch_execz .LBB0_562
	s_waitcnt lgkmcnt(0)
	v_add_f32_e32 v25, v25, v26
	v_cndmask_b32_e64 v25, 0, v25, s[4:5]
	global_store_dword v[2:3], v25, off
	s_branch .LBB0_562
